# mlstm_c: the tail's four head-norm weight loads also issued at the item-loop top
# speedup vs baseline: 1.0025x; 1.0025x over previous
; __device__ __forceinline__ float sigmoidf_(float x) { return __builtin_amdgcn_rcpf(1.f + __expf(-x)); }
; __device__ __forceinline__ void phase_mlstm_c(const Args& a, unsigned char* lds) {
;     ...
;         { const int t = tid >> 3, part = tid & 7, dv0 = part * 16;
;             const float den = fmaxf(fabsf(denS[t]), __expf(-mtS[t])); const float inv = 1.f / den;
;             float hv[16]; float sq = 0.f;
; #pragma unroll
;             for (int e = 0; e < 16; ++e) { hv[e] = OUT[t * 132 + dv0 + e] * inv; sq += hv[e] * hv[e]; }
;             sq += __shfl_xor(sq, 1); sq += __shfl_xor(sq, 2); sq += __shfl_xor(sq, 4);
;             const float rs = rsqrtf(sq * (1.f / 128.f) + EPS);
;             bf16_t* po = P + (r0 + t) * LDP + C_MO + h * 128 + dv0;
;             float og[16]; unpack8(*(const u32x4*)po, og); unpack8(*(const u32x4*)(po + 8), og + 8);
; #pragma unroll
;             for (int e = 0; e < 16; ++e) hv[e] = hv[e] * rs * a.in[I_MHN][h * 128 + dv0 + e] * sigmoidf_(og[e]);
;             *(u32x4*)po = pack8(hv); *(u32x4*)(po + 8) = pack8(hv + 8); }
.LBB0_794:
	s_or_b64 exec, exec, s[64:65]
	s_waitcnt lgkmcnt(0)
	s_barrier
	ds_read_b32 v0, v29
	ds_read_b32 v1, v28
	ds_read_b128 v[74:77], v30
	s_lshl_b32 s38, s91, 8
	v_lshlrev_b32_e32 v4, 1, v6
	s_waitcnt lgkmcnt(2)
	v_mul_f32_e32 v0, 0xbfb8aa3b, v0
	v_exp_f32_e32 v0, v0
	s_waitcnt lgkmcnt(1)
	v_max_f32_e64 v1, |v1|, |v1|
	s_add_i32 s62, s62, s72
	s_add_i32 s81, s81, s82
	v_max_f32_e32 v73, v1, v0
	v_div_scale_f32 v82, s[64:65], v73, v73, 1.0
	v_rcp_f32_e32 v86, v82
	v_mov_b64_e32 v[0:1], s[44:45]
	v_mad_u64_u32 v[0:1], s[64:65], v14, s88, v[0:1]
	v_fma_f32 v2, -v82, v86, 1.0
	v_fmac_f32_e32 v86, v2, v86
	v_mov_b32_e32 v2, v1
	v_mad_u64_u32 v[2:3], s[64:65], v15, s88, v[2:3]
	v_mov_b32_e32 v1, v2
	v_lshl_add_u64 v[0:1], v[0:1], 0, s[38:39]
	v_lshl_add_u64 v[2:3], v[0:1], 0, v[4:5]
	v_add_co_u32_e32 v0, vcc, s89, v2
	s_cmpk_lt_i32 s62, 0x1000
	s_nop 0
	v_addc_co_u32_e32 v1, vcc, 0, v3, vcc
	v_mov_b32_e32 v78, v220
	v_mov_b32_e32 v79, v221
	v_mov_b32_e32 v80, v222
	v_mov_b32_e32 v81, v223
	v_div_scale_f32 v4, vcc, 1.0, v73, 1.0
	v_mul_f32_e32 v14, v4, v86
	v_fma_f32 v15, -v82, v14, v4
	v_fmac_f32_e32 v14, v15, v86
	v_fma_f32 v4, -v82, v14, v4
	v_div_fmas_f32 v4, v4, v86, v14
	v_div_fixup_f32 v4, v4, v73, 1.0
	v_lshl_add_u64 v[2:3], v[2:3], 0, s[60:61]
	s_waitcnt lgkmcnt(0)
	v_mul_f32_e32 v104, v75, v4
	v_lshlrev_b32_e32 v14, 2, v6
	v_mov_b32_e32 v82, v224
	v_mov_b32_e32 v83, v225
	v_mov_b32_e32 v84, v226
	v_mov_b32_e32 v85, v227
	ds_read_b128 v[86:89], v30 offset:16
	ds_read_b128 v[90:93], v30 offset:32
	ds_read_b128 v[94:97], v30 offset:48
	v_mul_f32_e32 v73, v74, v4
	v_mul_f32_e32 v102, v104, v104
	v_lshl_or_b32 v106, s91, 9, v14
	v_fmac_f32_e32 v102, v73, v73
	v_mul_f32_e32 v105, v4, v76
	v_mov_b32_e32 v98, v204
	v_mov_b32_e32 v99, v205
	v_mov_b32_e32 v100, v206
	v_mov_b32_e32 v101, v207
	v_fmac_f32_e32 v102, v105, v105
	v_mul_f32_e32 v107, v4, v77
	v_fmac_f32_e32 v102, v107, v107
	s_waitcnt lgkmcnt(2)
	v_mul_f32_e32 v108, v4, v86
	v_fmac_f32_e32 v102, v108, v108
	v_mul_f32_e32 v109, v4, v87
	v_fmac_f32_e32 v102, v109, v109
	v_mul_f32_e32 v110, v4, v88
	v_fmac_f32_e32 v102, v110, v110
	v_mul_f32_e32 v111, v4, v89
	s_waitcnt lgkmcnt(1)
	v_pk_mul_f32 v[14:15], v[4:5], v[90:91] op_sel_hi:[0,1]
	v_fmac_f32_e32 v102, v111, v111
	v_pk_mul_f32 v[74:75], v[14:15], v[14:15]
	s_waitcnt lgkmcnt(0)
	v_pk_mul_f32 v[94:95], v[4:5], v[94:95] op_sel_hi:[0,1]
	v_add_f32_e32 v74, v74, v102
	v_pk_mul_f32 v[102:103], v[4:5], v[92:93] op_sel_hi:[0,1]
	v_add_f32_e32 v76, v75, v74
	v_pk_mul_f32 v[74:75], v[102:103], v[102:103]
	v_pk_mul_f32 v[96:97], v[4:5], v[96:97] op_sel_hi:[0,1]
	v_add_f32_e32 v74, v74, v76
	v_add_f32_e32 v76, v75, v74
	v_pk_mul_f32 v[74:75], v[94:95], v[94:95]
	s_waitcnt vmcnt(1)
	v_lshlrev_b32_e32 v112, 16, v82
	v_add_f32_e32 v74, v74, v76
	v_add_f32_e32 v76, v75, v74
	v_pk_mul_f32 v[74:75], v[96:97], v[96:97]
	v_and_b32_e32 v82, 0xffff0000, v82
	v_add_f32_e32 v4, v74, v76
	v_add_f32_e32 v4, v75, v4
	v_mov_b32_e32 v74, v208
	v_mov_b32_e32 v75, v209
	v_mov_b32_e32 v76, v210
	v_mov_b32_e32 v77, v211
	v_mov_b32_e32 v86, v212
	v_mov_b32_e32 v87, v213
	v_mov_b32_e32 v88, v214
	v_mov_b32_e32 v89, v215
	v_mov_b32_e32 v90, v216
	v_mov_b32_e32 v91, v217
	v_mov_b32_e32 v92, v218
	v_mov_b32_e32 v93, v219
	ds_bpermute_b32 v13, v13, v4
	v_lshlrev_b32_e32 v106, 16, v81
	v_and_b32_e32 v81, 0xffff0000, v81
	v_lshlrev_b32_e32 v113, 16, v83
	v_and_b32_e32 v83, 0xffff0000, v83
	s_waitcnt lgkmcnt(0)
	v_add_f32_e32 v4, v4, v13
	ds_bpermute_b32 v13, v71, v4
	v_and_b32_e32 v71, 0xffff0000, v78
	v_mul_f32_e32 v71, 0xbfb8aa3b, v71
	v_exp_f32_e32 v71, v71
	v_lshlrev_b32_e32 v114, 16, v84
	s_waitcnt lgkmcnt(0)
	v_add_f32_e32 v4, v4, v13
	ds_bpermute_b32 v13, v72, v4
	v_lshlrev_b32_e32 v72, 16, v79
	v_mul_f32_e32 v72, 0xbfb8aa3b, v72
	v_exp_f32_e32 v72, v72
	v_add_f32_e32 v71, 1.0, v71
	s_waitcnt lgkmcnt(0)
	v_add_f32_e32 v4, v4, v13
	v_fmamk_f32 v4, v4, 0x3c000000, v64
	v_mul_f32_e32 v13, 0x4b800000, v4
	v_cmp_gt_f32_e32 vcc, s90, v4
	v_rcp_f32_e32 v71, v71
	v_add_f32_e32 v72, 1.0, v72
	v_cndmask_b32_e32 v4, v4, v13, vcc
	v_rsq_f32_e32 v4, v4
	v_rcp_f32_e32 v72, v72
	v_and_b32_e32 v84, 0xffff0000, v84
	v_lshlrev_b32_e32 v115, 16, v85
	v_mul_f32_e32 v13, 0x45800000, v4
	v_cndmask_b32_e32 v4, v4, v13, vcc
	v_lshlrev_b32_e32 v13, 16, v78
	v_mul_f32_e32 v13, 0xbfb8aa3b, v13
	v_exp_f32_e32 v13, v13
	v_and_b32_e32 v78, 0xffff0000, v79
	v_mul_f32_e32 v78, 0xbfb8aa3b, v78
	v_exp_f32_e32 v78, v78
	v_add_f32_e32 v13, 1.0, v13
	v_rcp_f32_e32 v13, v13
	v_mul_f32_e32 v73, v73, v4
	s_waitcnt vmcnt(3)
	v_mul_f32_e32 v73, v98, v73
	v_add_f32_e32 v78, 1.0, v78
	v_mul_f32_e32 v13, v13, v73
	v_mul_f32_e32 v73, v104, v4
	v_mul_f32_e32 v73, v99, v73
	v_mul_f32_e32 v71, v71, v73
	v_mul_f32_e32 v73, v105, v4
	v_rcp_f32_e32 v78, v78
	v_mul_f32_e32 v73, v100, v73
	v_mul_f32_e32 v73, v72, v73
	v_mul_f32_e32 v72, v107, v4
	v_lshlrev_b32_e32 v79, 16, v80
	v_mul_f32_e32 v72, v101, v72
	v_mul_f32_e32 v78, v78, v72
	v_mul_f32_e32 v72, 0xbfb8aa3b, v79
	v_and_b32_e32 v80, 0xffff0000, v80
	v_exp_f32_e32 v72, v72
	v_mul_f32_e32 v80, 0xbfb8aa3b, v80
	v_exp_f32_e32 v80, v80
	v_mul_f32_e32 v79, v108, v4
	v_add_f32_e32 v72, 1.0, v72
	v_rcp_f32_e32 v72, v72
	v_mul_f32_e32 v14, v14, v4
	v_mul_f32_e32 v15, v15, v4
	v_and_b32_e32 v85, 0xffff0000, v85
	s_waitcnt vmcnt(2)
; __device__ __forceinline__ void phase_mlstm_c(const Args& a, unsigned char* lds) {
;     ...
;     for (int item = blockIdx.x; item < 4096; item += gridDim.x) {
;         const int c = item & 127, h = (item >> 7) & 3, b = item >> 9;
;         const size_t r0 = (size_t)b * SEQ + c * 64;
;         if (wave == 0) {
;             const float ig = SM[(r0 + lane) * 16 + 8 + h] + a.in[I_BI][h];
;             const float lf = logsigmoidf_(SM[(r0 + lane) * 16 + 12 + h] + a.in[I_BF][h]);
;             const float bs = wave_incl_sum(lf, lane);
;             const float av = ig - bs;
;             const float pm = wave_incl_max(av, lane);
;             const float m0 = MS[item];
;             const float mt = bs + fmaxf(pm, m0);
;             bS[lane] = bs; aS[lane] = av; mtS[lane] = mt; wiS[lane] = __expf(bs + m0 - mt);
;             nS[lane] = DN[item * 64 + lane];
;         }
;         { const int s = tid >> 3, d0 = (tid & 7) * 8;
;             *(u32x4*)(QS_ + s * 72 + d0) = *(const u32x4*)(QK + (r0 + s) * 512 + h * 64 + d0);
;             *(u32x4*)(KS + s * 72 + d0) = *(const u32x4*)(QK + (r0 + s) * 512 + 256 + h * 64 + d0); }
;         for (int i = tid; i < 1024; i += 512) { const int s = i >> 4, d0 = (i & 15) * 8; float f[8]; unpack8(*(const u32x4*)(P + (r0 + s) * LDP + C_MV + h * 128 + d0), f);
; #pragma unroll
;             for (int e = 0; e < 8; ++e) BT[(d0 + e) * 136 + s] = f2bf(f[e]); }
;         { const bf16_t* st = ST + (size_t)item * 8192;
;     ...
;         { const int t = tid >> 3, part = tid & 7, dv0 = part * 16;
;             const float den = fmaxf(fabsf(denS[t]), __expf(-mtS[t])); const float inv = 1.f / den;
;             float hv[16]; float sq = 0.f;
; #pragma unroll
;             for (int e = 0; e < 16; ++e) { hv[e] = OUT[t * 132 + dv0 + e] * inv; sq += hv[e] * hv[e]; }
;             sq += __shfl_xor(sq, 1); sq += __shfl_xor(sq, 2); sq += __shfl_xor(sq, 4);
;             const float rs = rsqrtf(sq * (1.f / 128.f) + EPS);
;             bf16_t* po = P + (r0 + t) * LDP + C_MO + h * 128 + dv0;
;             float og[16]; unpack8(*(const u32x4*)po, og); unpack8(*(const u32x4*)(po + 8), og + 8);
; #pragma unroll
;             for (int e = 0; e < 16; ++e) hv[e] = hv[e] * rs * a.in[I_MHN][h * 128 + dv0 + e] * sigmoidf_(og[e]);
;             *(u32x4*)po = pack8(hv); *(u32x4*)(po + 8) = pack8(hv + 8); }
;         __syncthreads();
	v_mul_f32_e32 v74, v74, v79
	v_add_f32_e32 v79, 1.0, v80
	v_rcp_f32_e32 v79, v79
	v_mul_f32_e32 v74, v72, v74
	v_mul_f32_e32 v72, v109, v4
	v_mul_f32_e32 v72, v75, v72
	v_mul_f32_e32 v75, v79, v72
	v_mul_f32_e32 v72, 0xbfb8aa3b, v106
	v_exp_f32_e32 v72, v72
	v_mul_f32_e32 v80, 0xbfb8aa3b, v81
	v_exp_f32_e32 v80, v80
	v_mul_f32_e32 v79, v110, v4
	v_add_f32_e32 v72, 1.0, v72
	v_rcp_f32_e32 v72, v72
	v_mul_f32_e32 v76, v76, v79
	v_add_f32_e32 v79, 1.0, v80
	v_rcp_f32_e32 v79, v79
	v_mul_f32_e32 v76, v72, v76
	v_mul_f32_e32 v72, v111, v4
	v_mul_f32_e32 v72, v77, v72
	v_mul_f32_e32 v77, v79, v72
	v_mul_f32_e32 v72, 0xbfb8aa3b, v112
	v_exp_f32_e32 v72, v72
	v_mul_f32_e32 v79, 0xbfb8aa3b, v82
	v_exp_f32_e32 v79, v79
	s_waitcnt vmcnt(0)
	v_mul_f32_e32 v14, v90, v14
	v_add_f32_e32 v72, 1.0, v72
	v_rcp_f32_e32 v72, v72
	v_mul_f32_e32 v80, 0xbfb8aa3b, v83
	v_add_f32_e32 v79, 1.0, v79
	v_exp_f32_e32 v80, v80
	v_mul_f32_e32 v14, v72, v14
	v_mul_f32_e32 v72, 0xbfb8aa3b, v113
	v_exp_f32_e32 v72, v72
	v_rcp_f32_e32 v79, v79
	v_mul_f32_e32 v15, v91, v15
	v_add_f32_e32 v80, 1.0, v80
	v_add_f32_e32 v72, 1.0, v72
	v_rcp_f32_e32 v72, v72
	v_mul_f32_e32 v15, v79, v15
	v_mul_f32_e32 v79, v102, v4
	v_rcp_f32_e32 v80, v80
	v_mul_f32_e32 v79, v79, v92
	v_mul_f32_e32 v79, v72, v79
	v_mul_f32_e32 v72, v103, v4
	v_mul_f32_e32 v72, v72, v93
	v_mul_f32_e32 v80, v80, v72
	v_mul_f32_e32 v72, 0xbfb8aa3b, v114
	v_exp_f32_e32 v72, v72
	v_mul_f32_e32 v82, 0xbfb8aa3b, v84
	v_exp_f32_e32 v82, v82
	v_mul_f32_e32 v81, v94, v4
	v_add_f32_e32 v72, 1.0, v72
	v_rcp_f32_e32 v72, v72
	v_add_f32_e32 v82, 1.0, v82
	v_rcp_f32_e32 v82, v82
	v_mul_f32_e32 v81, v81, v86
	v_mul_f32_e32 v81, v72, v81
	v_mul_f32_e32 v72, v95, v4
	v_mul_f32_e32 v72, v72, v87
	v_mul_f32_e32 v82, v82, v72
	v_mul_f32_e32 v72, 0xbfb8aa3b, v115
	v_exp_f32_e32 v72, v72
	v_mul_f32_e32 v84, 0xbfb8aa3b, v85
	v_exp_f32_e32 v84, v84
	v_mul_f32_e32 v83, v96, v4
	v_add_f32_e32 v72, 1.0, v72
	v_rcp_f32_e32 v72, v72
	v_add_f32_e32 v84, 1.0, v84
	v_rcp_f32_e32 v84, v84
	v_mul_f32_e32 v83, v83, v88
	v_mul_f32_e32 v4, v97, v4
	v_mul_f32_e32 v83, v72, v83
	v_mul_f32_e32 v4, v4, v89
	v_cvt_pk_bf16_f32 v72, v13, v71
	v_cvt_pk_bf16_f32 v73, v73, v78
	v_cvt_pk_bf16_f32 v74, v74, v75
	v_cvt_pk_bf16_f32 v75, v76, v77
	v_mul_f32_e32 v4, v84, v4
	global_store_dwordx4 v[0:1], v[72:75], off offset:640
	s_nop 1
	v_cvt_pk_bf16_f32 v72, v14, v15
	v_cvt_pk_bf16_f32 v73, v79, v80
	v_cvt_pk_bf16_f32 v74, v81, v82
	v_cvt_pk_bf16_f32 v75, v83, v4
	global_store_dwordx4 v[2:3], v[72:75], off offset:16
	s_barrier
	s_cbranch_scc0 .LBB0_855
.LBB0_795:
	s_ashr_i32 s64, s62, 9
	s_ashr_i32 s65, s64, 31
	s_lshl_b32 s92, s62, 6
	s_lshl_b64 s[64:65], s[64:65], 13
	s_and_b32 s33, s92, 0x1fc0
	s_ashr_i32 s63, s62, 31
	s_bfe_u32 s91, s62, 0x20007
	s_or_b32 s66, s64, s33
	s_mov_b32 s67, s65
	v_lshlrev_b32_e32 v250, 2, v6
	v_lshl_or_b32 v250, s91, 9, v250
	global_load_dwordx4 v[204:207], v250, s[52:53]
	global_load_dwordx4 v[208:211], v250, s[52:53] offset:16
	global_load_dwordx4 v[212:215], v250, s[52:53] offset:48
	global_load_dwordx4 v[216:219], v250, s[52:53] offset:32
	s_nop 0
	v_lshl_add_u64 v[252:253], s[66:67], 0, v[128:129]
	v_mov_b64_e32 v[248:249], s[44:45]
	v_mov_b32_e32 v251, v5
	v_mad_u64_u32 v[248:249], vcc, v252, s88, v[248:249]
	s_lshl_b32 s38, s91, 8
	v_mov_b32_e32 v250, v249
	v_mad_u64_u32 v[250:251], vcc, v253, s88, v[250:251]
	s_nop 0
	v_mov_b32_e32 v249, v250
	v_lshl_add_u64 v[248:249], v[248:249], 0, s[38:39]
	v_lshlrev_b32_e32 v250, 1, v6
	v_mov_b32_e32 v251, v5
	v_lshl_add_u64 v[250:251], v[248:249], 0, v[250:251]
	v_add_co_u32_e32 v248, vcc, s89, v250
	s_nop 1
	v_addc_co_u32_e32 v249, vcc, 0, v251, vcc
	global_load_dwordx4 v[220:223], v[248:249], off offset:640
	v_lshl_add_u64 v[252:253], v[250:251], 0, s[60:61]
	global_load_dwordx4 v[224:227], v[252:253], off offset:16
	s_nop 0
	v_lshl_add_u64 v[252:253], s[66:67], 0, v[128:129]
	v_lshlrev_b64 v[252:253], 10, v[252:253]
	v_lshl_add_u64 v[252:253], s[0:1], 0, v[252:253]
	s_lshl_b32 s38, s91, 7
	v_lshl_add_u64 v[252:253], v[252:253], 0, s[38:39]
	v_mov_b32_e32 v251, v5
	v_mov_b32_e32 v250, v12
	v_lshl_add_u64 v[252:253], v[252:253], 0, v[250:251]
	global_load_dwordx4 v[228:231], v[252:253], off
	global_load_dwordx4 v[232:235], v[252:253], off offset:512
	s_lshr_b32 s33, s62, 7
	s_and_b32 s38, s81, 0x1fc0
	s_and_b32 s33, s33, 3
	s_add_u32 s64, s38, s64
	s_addc_u32 s65, 0, s65
	v_lshl_add_u64 v[252:253], s[64:65], 0, v[16:17]
	v_mad_u64_u32 v[250:251], vcc, v252, s88, 0
	v_mad_i32_i24 v253, v253, s88, v251
	v_lshl_or_b32 v252, s33, 8, v250
	v_lshl_add_u64 v[252:253], v[8:9], 0, v[252:253]
	s_lshl_b64 s[94:95], s[62:63], 14
	global_load_dwordx4 v[236:239], v[252:253], off
	s_nop 0
	v_lshl_add_u64 v[252:253], v[252:253], 0, s[40:41]
	global_load_dwordx4 v[240:243], v[252:253], off
	s_nop 0
	v_lshl_add_u64 v[252:253], v[10:11], 0, s[94:95]
	global_load_dwordx4 v[244:247], v[252:253], off
	s_nop 0
	v_lshl_add_u64 v[252:253], v[252:253], 0, s[42:43]
	global_load_dwordx4 v[248:251], v[252:253], off
	s_and_saveexec_b64 s[76:77], s[4:5]
	s_cbranch_execz .LBB0_797
; __device__ __forceinline__ float logsigmoidf_(float x) { return fminf(x, 0.f) - log1pf(__expf(-fabsf(x))); }
; __device__ __forceinline__ void phase_mlstm_c(const Args& a, unsigned char* lds) {
;     ...
;         if (wave == 0) {
;             const float ig = SM[(r0 + lane) * 16 + 8 + h] + a.in[I_BI][h];
;             const float lf = logsigmoidf_(SM[(r0 + lane) * 16 + 12 + h] + a.in[I_BF][h]);
;             const float bs = wave_incl_sum(lf, lane);
;             const float av = ig - bs;
;             const float pm = wave_incl_max(av, lane);
;             const float m0 = MS[item];
;             const float mt = bs + fmaxf(pm, m0);
;             bS[lane] = bs; aS[lane] = av; mtS[lane] = mt; wiS[lane] = __expf(bs + m0 - mt);
;             nS[lane] = DN[item * 64 + lane];
;         }
	v_mov_b32_e32 v1, s67
	v_or_b32_e32 v0, s66, v156
	v_lshlrev_b64 v[0:1], 6, v[0:1]
	v_lshl_add_u64 v[0:1], s[58:59], 0, v[0:1]
	s_lshl_b32 s38, s91, 2
	v_lshl_add_u64 v[0:1], v[0:1], 0, s[38:39]
	v_mov_b32_e32 v2, s38
	global_load_dword v3, v[0:1], off offset:48
	global_load_dword v4, v2, s[50:51]
	s_nop 0
	global_load_dword v2, v2, s[48:49]
	s_nop 0
	global_load_dword v13, v[0:1], off offset:32
	s_lshl_b64 s[94:95], s[62:63], 2
	v_or_b32_e32 v0, s92, v156
	s_add_u32 s92, s78, s94
	v_ashrrev_i32_e32 v1, 31, v0
	s_addc_u32 s93, s79, s95
	v_lshl_add_u64 v[0:1], v[0:1], 2, s[36:37]
	global_load_dword v77, v5, s[92:93]
	global_load_dword v78, v[0:1], off
	v_mov_b32_e32 v14, v5
	v_mov_b32_e32 v15, v5
	v_mov_b32_e32 v71, 0xff800000
	v_mov_b32_e32 v72, 0xff800000
	v_mov_b32_e32 v73, 0xff800000
	v_mov_b32_e32 v74, 0xff800000
	v_mov_b32_e32 v75, 0xff800000
	v_mov_b32_e32 v76, 0xff800000
	s_waitcnt vmcnt(4)
	v_add_f32_e32 v3, v3, v4
	v_mul_f32_e64 v4, |v3|, s83
	v_exp_f32_e32 v4, v4
	s_waitcnt vmcnt(2)
	v_add_f32_e32 v2, v13, v2
	v_min_f32_e32 v3, 0, v3
	v_add_f32_e32 v13, 1.0, v4
	v_add_f32_e32 v79, -1.0, v13
	v_frexp_mant_f32_e32 v80, v13
	v_cvt_f64_f32_e32 v[0:1], v13
	v_sub_f32_e32 v81, v79, v13
	v_frexp_exp_i32_f64_e32 v0, v[0:1]
	v_cmp_gt_f32_e32 vcc, s84, v80
	v_sub_f32_e32 v79, v4, v79
	v_add_f32_e32 v1, 1.0, v81
	v_subbrev_co_u32_e32 v0, vcc, 0, v0, vcc
	v_add_f32_e32 v1, v79, v1
	v_sub_u32_e32 v79, 0, v0
	v_cvt_f32_i32_e32 v0, v0
	v_ldexp_f32 v13, v13, v79
	v_ldexp_f32 v1, v1, v79
	v_add_f32_e32 v79, -1.0, v13
	v_add_f32_e32 v80, 1.0, v13
	v_add_f32_e32 v81, 1.0, v79
	v_add_f32_e32 v82, -1.0, v80
	v_sub_f32_e32 v81, v13, v81
	v_sub_f32_e32 v13, v13, v82
	v_mul_f32_e32 v82, 0x3f317218, v0
	v_add_f32_e32 v81, v1, v81
	v_add_f32_e32 v1, v1, v13
	v_fma_f32 v13, v0, s85, -v82
	v_add_f32_e32 v83, v79, v81
	v_add_f32_e32 v84, v80, v1
	v_fmac_f32_e32 v13, 0xb102e308, v0
	v_sub_f32_e32 v0, v83, v79
	v_sub_f32_e32 v79, v84, v80
	v_rcp_f32_e32 v80, v84
	v_add_f32_e32 v85, v82, v13
	v_sub_f32_e32 v1, v1, v79
	v_sub_f32_e32 v79, v85, v82
	v_sub_f32_e32 v13, v13, v79
	v_mul_f32_e32 v79, v83, v80
	v_sub_f32_e32 v0, v81, v0
	v_mul_f32_e32 v81, v84, v79
	v_fma_f32 v82, v79, v84, -v81
	v_fmac_f32_e32 v82, v79, v1
	v_add_f32_e32 v86, v81, v82
	v_sub_f32_e32 v87, v83, v86
	v_sub_f32_e32 v81, v86, v81
	v_sub_f32_e32 v83, v83, v87
	v_sub_f32_e32 v81, v81, v82
	v_sub_f32_e32 v82, v83, v86
	v_add_f32_e32 v0, v0, v82
	v_add_f32_e32 v0, v81, v0
	v_add_f32_e32 v81, v87, v0
	v_mul_f32_e32 v82, v80, v81
	v_sub_f32_e32 v83, v87, v81
	v_mul_f32_e32 v86, v84, v82
	v_add_f32_e32 v0, v0, v83
	v_add_f32_e32 v83, v79, v82
	v_fma_f32 v84, v82, v84, -v86
	v_sub_f32_e32 v79, v83, v79
	v_fmac_f32_e32 v84, v82, v1
	v_sub_f32_e32 v1, v82, v79
	v_add_f32_e32 v79, v86, v84
	v_sub_f32_e32 v82, v79, v86
	v_sub_f32_e32 v86, v81, v79
	v_sub_f32_e32 v81, v81, v86
	v_sub_f32_e32 v79, v81, v79
	v_sub_f32_e32 v82, v82, v84
	v_add_f32_e32 v0, v0, v79
	v_add_f32_e32 v0, v82, v0
	v_add_f32_e32 v0, v86, v0
	v_mul_f32_e32 v0, v80, v0
	v_add_f32_e32 v0, v1, v0
	v_add_f32_e32 v1, v83, v0
	v_mul_f32_e32 v79, v1, v1
	v_fmamk_f32 v82, v79, 0x3e9b6dac, v61
	v_sub_f32_e32 v80, v1, v83
	v_ldexp_f32 v81, v1, 1
	v_mul_f32_e32 v1, v1, v79
	v_fmaak_f32 v79, v79, v82, 0x3f2aaada
	v_mul_f32_e32 v1, v1, v79
	v_add_f32_e32 v79, v81, v1
	v_sub_f32_e32 v0, v0, v80
	v_sub_f32_e32 v80, v79, v81
	v_ldexp_f32 v0, v0, 1
	v_sub_f32_e32 v1, v1, v80
	v_add_f32_e32 v0, v0, v1
	v_add_f32_e32 v1, v79, v0
	v_sub_f32_e32 v79, v1, v79
	v_add_f32_e32 v80, v85, v1
	v_sub_f32_e32 v0, v0, v79
	v_sub_f32_e32 v79, v80, v85
	v_sub_f32_e32 v81, v80, v79
	v_sub_f32_e32 v1, v1, v79
	v_add_f32_e32 v79, v13, v0
	v_sub_f32_e32 v81, v85, v81
	v_sub_f32_e32 v82, v79, v13
	v_add_f32_e32 v1, v1, v81
	v_sub_f32_e32 v81, v79, v82
	v_sub_f32_e32 v0, v0, v82
	v_sub_f32_e32 v13, v13, v81
	v_add_f32_e32 v1, v79, v1
	v_add_f32_e32 v0, v0, v13
	v_add_f32_e32 v13, v80, v1
	v_sub_f32_e32 v79, v13, v80
	v_sub_f32_e32 v1, v1, v79
	v_add_f32_e32 v0, v0, v1
	v_add_f32_e32 v0, v13, v0
	v_cmp_neq_f32_e32 vcc, s86, v4
	s_nop 1
	v_cndmask_b32_e32 v0, v65, v0, vcc
	v_cmp_ngt_f32_e32 vcc, -1.0, v4
	s_nop 1
	v_cndmask_b32_e32 v0, v66, v0, vcc
	v_cmp_neq_f32_e32 vcc, -1.0, v4
	s_nop 1
	v_cndmask_b32_e32 v0, v62, v0, vcc
	v_cmp_lt_f32_e64 vcc, |v4|, s87
	s_nop 1
	v_cndmask_b32_e32 v0, v0, v4, vcc
	v_sub_f32_e32 v0, v3, v0
	s_nop 1
	v_add_f32_dpp v0, v0, v0 row_shr:1 row_mask:0xf bank_mask:0xf bound_ctrl:1
	s_nop 1
	v_add_f32_dpp v0, v0, v0 row_shr:2 row_mask:0xf bank_mask:0xf bound_ctrl:1
	s_nop 1
	v_add_f32_dpp v0, v0, v0 row_shr:4 row_mask:0xf bank_mask:0xf bound_ctrl:1
	s_nop 1
	v_add_f32_dpp v0, v0, v0 row_shr:8 row_mask:0xf bank_mask:0xf bound_ctrl:1
	s_nop 1
	v_mov_b32_dpp v14, v0 row_bcast:15 row_mask:0xa bank_mask:0xf
	v_add_f32_e32 v0, v0, v14
	s_nop 1
	v_mov_b32_dpp v15, v0 row_bcast:31 row_mask:0xc bank_mask:0xf
	v_add_f32_e32 v0, v0, v15
	v_sub_f32_e32 v1, v2, v0
	s_waitcnt vmcnt(1)
	v_add_f32_e32 v2, v77, v0
	v_mov_b32_dpp v71, v1 row_shr:1 row_mask:0xf bank_mask:0xf
	v_max_f32_e32 v3, v71, v71
	v_max_f32_e32 v3, v1, v3
	s_nop 1
	v_mov_b32_dpp v72, v3 row_shr:2 row_mask:0xf bank_mask:0xf
	v_max_f32_e32 v4, v72, v72
	v_max_f32_e32 v3, v3, v4
	s_nop 1
	v_mov_b32_dpp v73, v3 row_shr:4 row_mask:0xf bank_mask:0xf
	v_max_f32_e32 v4, v73, v73
	v_max_f32_e32 v3, v3, v4
	s_nop 1
	v_mov_b32_dpp v74, v3 row_shr:8 row_mask:0xf bank_mask:0xf
	v_max_f32_e32 v4, v74, v74
	v_max_f32_e32 v3, v3, v4
	s_nop 1
	v_mov_b32_dpp v75, v3 row_bcast:15 row_mask:0xa bank_mask:0xf
	v_max_f32_e32 v4, v75, v75
	v_max_f32_e32 v3, v3, v4
	s_nop 1
	v_mov_b32_dpp v76, v3 row_bcast:31 row_mask:0xc bank_mask:0xf
	v_max3_f32 v3, v3, v76, v77
	v_add_f32_e32 v3, v0, v3
	v_sub_f32_e32 v2, v2, v3
	v_mul_f32_e32 v2, 0x3fb8aa3b, v2
	v_exp_f32_e32 v2, v2
	ds_write_b32 v7, v0
	ds_write_b32 v18, v1
	ds_write_b32 v19, v3
	ds_write_b32 v20, v2
	s_waitcnt vmcnt(0)
	ds_write_b32 v21, v78
